# scan step: packed fp32 FMAs feeding the MFMA accumulators split into scalar v_fma_f32 (asm guide 7.5), bit-identical
# speedup vs baseline: 1.0052x; 1.0012x over previous
; DI void phase_scan(KArgs args, LAS unsigned char* L, const Ctx& c) {
;     ...
;         for (int step = 0; step < nch; step += 2) {
;             SCAN_STEP(0, step);     asm volatile("s_waitcnt vmcnt(24)" ::: "memory"); SCAN_LOAD(0); SCAN_DMA();
;             SCAN_STEP(1, step + 1); asm volatile("s_waitcnt vmcnt(24)" ::: "memory"); SCAN_LOAD(1); SCAN_DMA();
;         }
.Lscan_loop:
	s_waitcnt vmcnt(32)
	s_lshr_b32 s6, s10, 6
	s_cmp_lt_u32 s10, 64
	s_cselect_b64 vcc, -1, 0
	s_cmp_eq_u32 s6, 1
	s_cselect_b64 s[4:5], -1, 0
	s_cmp_eq_u32 s6, 2
	s_cselect_b64 s[6:7], -1, 0
	v_cndmask_b32_e64 v172, v170, v169, s[6:7]
	v_cndmask_b32_e64 v172, v172, v168, s[4:5]
	v_cndmask_b32_e32 v172, v172, v1, vcc
	v_cvt_pk_bf16_f32 v132, v4, v5
	v_cvt_pk_bf16_f32 v133, v6, v7
	v_cvt_pk_bf16_f32 v134, v8, v9
	v_cvt_pk_bf16_f32 v135, v10, v11
	v_cvt_pk_bf16_f32 v136, v12, v13
	v_cvt_pk_bf16_f32 v137, v14, v15
	v_cvt_pk_bf16_f32 v138, v16, v17
	v_cvt_pk_bf16_f32 v139, v18, v19
	v_cvt_pk_bf16_f32 v140, v20, v21
	v_cvt_pk_bf16_f32 v141, v22, v23
	v_cvt_pk_bf16_f32 v142, v24, v25
	v_cvt_pk_bf16_f32 v143, v26, v27
	v_cvt_pk_bf16_f32 v144, v28, v29
	v_cvt_pk_bf16_f32 v145, v30, v31
	v_cvt_pk_bf16_f32 v146, v32, v33
	v_cvt_pk_bf16_f32 v147, v34, v35
	v_readlane_b32 s4, v172, s10
	global_store_dwordx4 v[166:167], v[132:135], off offset:-2048
	global_store_dwordx4 v[166:167], v[136:139], off offset:-1024
	global_store_dwordx4 v[166:167], v[140:143], off
	global_store_dwordx4 v[166:167], v[144:147], off offset:1024
	v_lshlrev_b32_e32 v174, 16, v68
	v_and_b32_e32 v175, 0xffff0000, v68
	v_fma_f32 v4, v4, s4, v174
	v_fma_f32 v5, v5, s4, v175
	v_lshlrev_b32_e32 v174, 16, v69
	v_and_b32_e32 v175, 0xffff0000, v69
	v_fma_f32 v6, v6, s4, v174
	v_fma_f32 v7, v7, s4, v175
	v_lshlrev_b32_e32 v174, 16, v70
	v_and_b32_e32 v175, 0xffff0000, v70
	v_fma_f32 v8, v8, s4, v174
	v_fma_f32 v9, v9, s4, v175
	v_lshlrev_b32_e32 v174, 16, v71
	v_and_b32_e32 v175, 0xffff0000, v71
	v_fma_f32 v10, v10, s4, v174
	v_fma_f32 v11, v11, s4, v175
	v_lshlrev_b32_e32 v174, 16, v72
	v_and_b32_e32 v175, 0xffff0000, v72
	v_fma_f32 v12, v12, s4, v174
	v_fma_f32 v13, v13, s4, v175
	v_lshlrev_b32_e32 v174, 16, v73
	v_and_b32_e32 v175, 0xffff0000, v73
	v_fma_f32 v14, v14, s4, v174
	v_fma_f32 v15, v15, s4, v175
	v_lshlrev_b32_e32 v174, 16, v74
	v_and_b32_e32 v175, 0xffff0000, v74
	v_fma_f32 v16, v16, s4, v174
	v_fma_f32 v17, v17, s4, v175
	v_lshlrev_b32_e32 v174, 16, v75
	v_and_b32_e32 v175, 0xffff0000, v75
	v_fma_f32 v18, v18, s4, v174
	v_fma_f32 v19, v19, s4, v175
	v_lshlrev_b32_e32 v174, 16, v76
	v_and_b32_e32 v175, 0xffff0000, v76
	v_fma_f32 v20, v20, s4, v174
	v_fma_f32 v21, v21, s4, v175
	v_lshlrev_b32_e32 v174, 16, v77
	v_and_b32_e32 v175, 0xffff0000, v77
	v_fma_f32 v22, v22, s4, v174
	v_fma_f32 v23, v23, s4, v175
	v_lshlrev_b32_e32 v174, 16, v78
	v_and_b32_e32 v175, 0xffff0000, v78
	v_fma_f32 v24, v24, s4, v174
	v_fma_f32 v25, v25, s4, v175
	v_lshlrev_b32_e32 v174, 16, v79
	v_and_b32_e32 v175, 0xffff0000, v79
	v_fma_f32 v26, v26, s4, v174
	v_fma_f32 v27, v27, s4, v175
	v_lshlrev_b32_e32 v174, 16, v80
	v_and_b32_e32 v175, 0xffff0000, v80
	v_fma_f32 v28, v28, s4, v174
	v_fma_f32 v29, v29, s4, v175
	v_lshlrev_b32_e32 v174, 16, v81
	v_and_b32_e32 v175, 0xffff0000, v81
	v_fma_f32 v30, v30, s4, v174
	v_fma_f32 v31, v31, s4, v175
	v_lshlrev_b32_e32 v174, 16, v82
	v_and_b32_e32 v175, 0xffff0000, v82
	v_fma_f32 v32, v32, s4, v174
	v_fma_f32 v33, v33, s4, v175
	v_lshlrev_b32_e32 v174, 16, v83
	v_and_b32_e32 v175, 0xffff0000, v83
	v_fma_f32 v34, v34, s4, v174
	v_fma_f32 v35, v35, s4, v175
	s_nop 1
	v_mfma_f32_32x32x16_bf16 v[4:19], v[36:39], v[132:135], v[4:19]
	v_mfma_f32_32x32x16_bf16 v[20:35], v[52:55], v[132:135], v[20:35]
	v_mfma_f32_32x32x16_bf16 v[4:19], v[40:43], v[136:139], v[4:19]
	v_mfma_f32_32x32x16_bf16 v[20:35], v[56:59], v[136:139], v[20:35]
	v_mfma_f32_32x32x16_bf16 v[4:19], v[44:47], v[140:143], v[4:19]
	v_mfma_f32_32x32x16_bf16 v[20:35], v[60:63], v[140:143], v[20:35]
	v_mfma_f32_32x32x16_bf16 v[4:19], v[48:51], v[144:147], v[4:19]
	v_mfma_f32_32x32x16_bf16 v[20:35], v[64:67], v[144:147], v[20:35]
	v_lshl_add_u64 v[166:167], v[166:167], 0, s[0:1]
	s_add_u32 s14, s12, 0x1000
	s_addc_u32 s15, s13, 0
	s_add_u32 s16, s12, 0x2000
	s_addc_u32 s17, s13, 0
	global_load_dwordx4 v[36:39], v2, s[12:13]
	global_load_dwordx4 v[40:43], v2, s[12:13] offset:1024
	global_load_dwordx4 v[44:47], v2, s[12:13] offset:2048
	global_load_dwordx4 v[48:51], v2, s[12:13] offset:3072
	global_load_dwordx4 v[52:55], v2, s[14:15]
	global_load_dwordx4 v[56:59], v2, s[14:15] offset:1024
	global_load_dwordx4 v[60:63], v2, s[14:15] offset:2048
	global_load_dwordx4 v[64:67], v2, s[14:15] offset:3072
	global_load_dwordx4 v[68:71], v162, s[16:17]
	global_load_dwordx4 v[72:75], v162, s[16:17] offset:16
	global_load_dwordx4 v[76:79], v164, s[16:17]
	global_load_dwordx4 v[80:83], v164, s[16:17] offset:16
	s_add_i32 s11, s11, 1
	s_cmp_le_u32 s11, s31
	s_cselect_b32 s6, s0, 0
	s_cselect_b32 s7, s1, 0
	s_add_u32 s12, s12, s6
	s_addc_u32 s13, s13, s7
	s_add_i32 s10, s10, 1
	s_cmp_ge_u32 s10, s30
	s_cbranch_scc1 .Lscan_exit
; DI void phase_scan(KArgs args, LAS unsigned char* L, const Ctx& c) {
;     ...
;         for (int step = 0; step < nch; step += 2) {
;             SCAN_STEP(0, step);     asm volatile("s_waitcnt vmcnt(24)" ::: "memory"); SCAN_LOAD(0); SCAN_DMA();
;             SCAN_STEP(1, step + 1); asm volatile("s_waitcnt vmcnt(24)" ::: "memory"); SCAN_LOAD(1); SCAN_DMA();
;         }
	s_waitcnt vmcnt(32)
	s_lshr_b32 s6, s10, 6
	s_cmp_lt_u32 s10, 64
	s_cselect_b64 vcc, -1, 0
	s_cmp_eq_u32 s6, 1
	s_cselect_b64 s[4:5], -1, 0
	s_cmp_eq_u32 s6, 2
	s_cselect_b64 s[6:7], -1, 0
	v_cndmask_b32_e64 v172, v170, v169, s[6:7]
	v_cndmask_b32_e64 v172, v172, v168, s[4:5]
	v_cndmask_b32_e32 v172, v172, v1, vcc
	v_cvt_pk_bf16_f32 v132, v4, v5
	v_cvt_pk_bf16_f32 v133, v6, v7
	v_cvt_pk_bf16_f32 v134, v8, v9
	v_cvt_pk_bf16_f32 v135, v10, v11
	v_cvt_pk_bf16_f32 v136, v12, v13
	v_cvt_pk_bf16_f32 v137, v14, v15
	v_cvt_pk_bf16_f32 v138, v16, v17
	v_cvt_pk_bf16_f32 v139, v18, v19
	v_cvt_pk_bf16_f32 v140, v20, v21
	v_cvt_pk_bf16_f32 v141, v22, v23
	v_cvt_pk_bf16_f32 v142, v24, v25
	v_cvt_pk_bf16_f32 v143, v26, v27
	v_cvt_pk_bf16_f32 v144, v28, v29
	v_cvt_pk_bf16_f32 v145, v30, v31
	v_cvt_pk_bf16_f32 v146, v32, v33
	v_cvt_pk_bf16_f32 v147, v34, v35
	v_readlane_b32 s4, v172, s10
	global_store_dwordx4 v[166:167], v[132:135], off offset:-2048
	global_store_dwordx4 v[166:167], v[136:139], off offset:-1024
	global_store_dwordx4 v[166:167], v[140:143], off
	global_store_dwordx4 v[166:167], v[144:147], off offset:1024
	v_lshlrev_b32_e32 v174, 16, v116
	v_and_b32_e32 v175, 0xffff0000, v116
	v_fma_f32 v4, v4, s4, v174
	v_fma_f32 v5, v5, s4, v175
	v_lshlrev_b32_e32 v174, 16, v117
	v_and_b32_e32 v175, 0xffff0000, v117
	v_fma_f32 v6, v6, s4, v174
	v_fma_f32 v7, v7, s4, v175
	v_lshlrev_b32_e32 v174, 16, v118
	v_and_b32_e32 v175, 0xffff0000, v118
	v_fma_f32 v8, v8, s4, v174
	v_fma_f32 v9, v9, s4, v175
	v_lshlrev_b32_e32 v174, 16, v119
	v_and_b32_e32 v175, 0xffff0000, v119
	v_fma_f32 v10, v10, s4, v174
	v_fma_f32 v11, v11, s4, v175
	v_lshlrev_b32_e32 v174, 16, v120
	v_and_b32_e32 v175, 0xffff0000, v120
	v_fma_f32 v12, v12, s4, v174
	v_fma_f32 v13, v13, s4, v175
	v_lshlrev_b32_e32 v174, 16, v121
	v_and_b32_e32 v175, 0xffff0000, v121
	v_fma_f32 v14, v14, s4, v174
	v_fma_f32 v15, v15, s4, v175
	v_lshlrev_b32_e32 v174, 16, v122
	v_and_b32_e32 v175, 0xffff0000, v122
	v_fma_f32 v16, v16, s4, v174
	v_fma_f32 v17, v17, s4, v175
	v_lshlrev_b32_e32 v174, 16, v123
	v_and_b32_e32 v175, 0xffff0000, v123
	v_fma_f32 v18, v18, s4, v174
	v_fma_f32 v19, v19, s4, v175
	v_lshlrev_b32_e32 v174, 16, v124
	v_and_b32_e32 v175, 0xffff0000, v124
	v_fma_f32 v20, v20, s4, v174
	v_fma_f32 v21, v21, s4, v175
	v_lshlrev_b32_e32 v174, 16, v125
	v_and_b32_e32 v175, 0xffff0000, v125
	v_fma_f32 v22, v22, s4, v174
	v_fma_f32 v23, v23, s4, v175
	v_lshlrev_b32_e32 v174, 16, v126
	v_and_b32_e32 v175, 0xffff0000, v126
	v_fma_f32 v24, v24, s4, v174
	v_fma_f32 v25, v25, s4, v175
	v_lshlrev_b32_e32 v174, 16, v127
	v_and_b32_e32 v175, 0xffff0000, v127
	v_fma_f32 v26, v26, s4, v174
	v_fma_f32 v27, v27, s4, v175
	v_lshlrev_b32_e32 v174, 16, v128
	v_and_b32_e32 v175, 0xffff0000, v128
	v_fma_f32 v28, v28, s4, v174
	v_fma_f32 v29, v29, s4, v175
	v_lshlrev_b32_e32 v174, 16, v129
	v_and_b32_e32 v175, 0xffff0000, v129
	v_fma_f32 v30, v30, s4, v174
	v_fma_f32 v31, v31, s4, v175
	v_lshlrev_b32_e32 v174, 16, v130
	v_and_b32_e32 v175, 0xffff0000, v130
	v_fma_f32 v32, v32, s4, v174
	v_fma_f32 v33, v33, s4, v175
	v_lshlrev_b32_e32 v174, 16, v131
	v_and_b32_e32 v175, 0xffff0000, v131
	v_fma_f32 v34, v34, s4, v174
	v_fma_f32 v35, v35, s4, v175
	s_nop 1
	v_mfma_f32_32x32x16_bf16 v[4:19], v[84:87], v[132:135], v[4:19]
	v_mfma_f32_32x32x16_bf16 v[20:35], v[100:103], v[132:135], v[20:35]
	v_mfma_f32_32x32x16_bf16 v[4:19], v[88:91], v[136:139], v[4:19]
	v_mfma_f32_32x32x16_bf16 v[20:35], v[104:107], v[136:139], v[20:35]
	v_mfma_f32_32x32x16_bf16 v[4:19], v[92:95], v[140:143], v[4:19]
	v_mfma_f32_32x32x16_bf16 v[20:35], v[108:111], v[140:143], v[20:35]
	v_mfma_f32_32x32x16_bf16 v[4:19], v[96:99], v[144:147], v[4:19]
	v_mfma_f32_32x32x16_bf16 v[20:35], v[112:115], v[144:147], v[20:35]
	v_lshl_add_u64 v[166:167], v[166:167], 0, s[0:1]
	s_add_u32 s14, s12, 0x1000
	s_addc_u32 s15, s13, 0
	s_add_u32 s16, s12, 0x2000
	s_addc_u32 s17, s13, 0
	global_load_dwordx4 v[84:87], v2, s[12:13]
	global_load_dwordx4 v[88:91], v2, s[12:13] offset:1024
	global_load_dwordx4 v[92:95], v2, s[12:13] offset:2048
	global_load_dwordx4 v[96:99], v2, s[12:13] offset:3072
	global_load_dwordx4 v[100:103], v2, s[14:15]
	global_load_dwordx4 v[104:107], v2, s[14:15] offset:1024
	global_load_dwordx4 v[108:111], v2, s[14:15] offset:2048
	global_load_dwordx4 v[112:115], v2, s[14:15] offset:3072
	global_load_dwordx4 v[116:119], v162, s[16:17]
	global_load_dwordx4 v[120:123], v162, s[16:17] offset:16
	global_load_dwordx4 v[124:127], v164, s[16:17]
	global_load_dwordx4 v[128:131], v164, s[16:17] offset:16
	s_add_i32 s11, s11, 1
	s_cmp_le_u32 s11, s31
	s_cselect_b32 s6, s0, 0
	s_cselect_b32 s7, s1, 0
	s_add_u32 s12, s12, s6
	s_addc_u32 s13, s13, s7
	s_add_i32 s10, s10, 1
	s_cmp_ge_u32 s10, s30
	s_cbranch_scc1 .Lscan_exit
; DI void phase_scan(KArgs args, LAS unsigned char* L, const Ctx& c) {
;     ...
;         for (int step = 0; step < nch; step += 2) {
;             SCAN_STEP(0, step);     asm volatile("s_waitcnt vmcnt(24)" ::: "memory"); SCAN_LOAD(0); SCAN_DMA();
;             SCAN_STEP(1, step + 1); asm volatile("s_waitcnt vmcnt(24)" ::: "memory"); SCAN_LOAD(1); SCAN_DMA();
;         }
	s_waitcnt vmcnt(32)
	s_lshr_b32 s6, s10, 6
	s_cmp_lt_u32 s10, 64
	s_cselect_b64 vcc, -1, 0
	s_cmp_eq_u32 s6, 1
	s_cselect_b64 s[4:5], -1, 0
	s_cmp_eq_u32 s6, 2
	s_cselect_b64 s[6:7], -1, 0
	v_cndmask_b32_e64 v172, v170, v169, s[6:7]
	v_cndmask_b32_e64 v172, v172, v168, s[4:5]
	v_cndmask_b32_e32 v172, v172, v1, vcc
	v_cvt_pk_bf16_f32 v132, v4, v5
	v_cvt_pk_bf16_f32 v133, v6, v7
	v_cvt_pk_bf16_f32 v134, v8, v9
	v_cvt_pk_bf16_f32 v135, v10, v11
	v_cvt_pk_bf16_f32 v136, v12, v13
	v_cvt_pk_bf16_f32 v137, v14, v15
	v_cvt_pk_bf16_f32 v138, v16, v17
	v_cvt_pk_bf16_f32 v139, v18, v19
	v_cvt_pk_bf16_f32 v140, v20, v21
	v_cvt_pk_bf16_f32 v141, v22, v23
	v_cvt_pk_bf16_f32 v142, v24, v25
	v_cvt_pk_bf16_f32 v143, v26, v27
	v_cvt_pk_bf16_f32 v144, v28, v29
	v_cvt_pk_bf16_f32 v145, v30, v31
	v_cvt_pk_bf16_f32 v146, v32, v33
	v_cvt_pk_bf16_f32 v147, v34, v35
	v_readlane_b32 s4, v172, s10
	global_store_dwordx4 v[166:167], v[132:135], off offset:-2048
	global_store_dwordx4 v[166:167], v[136:139], off offset:-1024
	global_store_dwordx4 v[166:167], v[140:143], off
	global_store_dwordx4 v[166:167], v[144:147], off offset:1024
	v_lshlrev_b32_e32 v174, 16, v230
	v_and_b32_e32 v175, 0xffff0000, v230
	v_fma_f32 v4, v4, s4, v174
	v_fma_f32 v5, v5, s4, v175
	v_lshlrev_b32_e32 v174, 16, v231
	v_and_b32_e32 v175, 0xffff0000, v231
	v_fma_f32 v6, v6, s4, v174
	v_fma_f32 v7, v7, s4, v175
	v_lshlrev_b32_e32 v174, 16, v232
	v_and_b32_e32 v175, 0xffff0000, v232
	v_fma_f32 v8, v8, s4, v174
	v_fma_f32 v9, v9, s4, v175
	v_lshlrev_b32_e32 v174, 16, v233
	v_and_b32_e32 v175, 0xffff0000, v233
	v_fma_f32 v10, v10, s4, v174
	v_fma_f32 v11, v11, s4, v175
	v_lshlrev_b32_e32 v174, 16, v234
	v_and_b32_e32 v175, 0xffff0000, v234
	v_fma_f32 v12, v12, s4, v174
	v_fma_f32 v13, v13, s4, v175
	v_lshlrev_b32_e32 v174, 16, v235
	v_and_b32_e32 v175, 0xffff0000, v235
	v_fma_f32 v14, v14, s4, v174
	v_fma_f32 v15, v15, s4, v175
	v_lshlrev_b32_e32 v174, 16, v236
	v_and_b32_e32 v175, 0xffff0000, v236
	v_fma_f32 v16, v16, s4, v174
	v_fma_f32 v17, v17, s4, v175
	v_lshlrev_b32_e32 v174, 16, v237
	v_and_b32_e32 v175, 0xffff0000, v237
	v_fma_f32 v18, v18, s4, v174
	v_fma_f32 v19, v19, s4, v175
	v_lshlrev_b32_e32 v174, 16, v238
	v_and_b32_e32 v175, 0xffff0000, v238
	v_fma_f32 v20, v20, s4, v174
	v_fma_f32 v21, v21, s4, v175
	v_lshlrev_b32_e32 v174, 16, v239
	v_and_b32_e32 v175, 0xffff0000, v239
	v_fma_f32 v22, v22, s4, v174
	v_fma_f32 v23, v23, s4, v175
	v_lshlrev_b32_e32 v174, 16, v240
	v_and_b32_e32 v175, 0xffff0000, v240
	v_fma_f32 v24, v24, s4, v174
	v_fma_f32 v25, v25, s4, v175
	v_lshlrev_b32_e32 v174, 16, v241
	v_and_b32_e32 v175, 0xffff0000, v241
	v_fma_f32 v26, v26, s4, v174
	v_fma_f32 v27, v27, s4, v175
	v_lshlrev_b32_e32 v174, 16, v242
	v_and_b32_e32 v175, 0xffff0000, v242
	v_fma_f32 v28, v28, s4, v174
	v_fma_f32 v29, v29, s4, v175
	v_lshlrev_b32_e32 v174, 16, v243
	v_and_b32_e32 v175, 0xffff0000, v243
	v_fma_f32 v30, v30, s4, v174
	v_fma_f32 v31, v31, s4, v175
	v_lshlrev_b32_e32 v174, 16, v244
	v_and_b32_e32 v175, 0xffff0000, v244
	v_fma_f32 v32, v32, s4, v174
	v_fma_f32 v33, v33, s4, v175
	v_lshlrev_b32_e32 v174, 16, v245
	v_and_b32_e32 v175, 0xffff0000, v245
	v_fma_f32 v34, v34, s4, v174
	v_fma_f32 v35, v35, s4, v175
	s_nop 1
	v_mfma_f32_32x32x16_bf16 v[4:19], v[178:181], v[132:135], v[4:19]
	v_mfma_f32_32x32x16_bf16 v[20:35], v[194:197], v[132:135], v[20:35]
	v_mfma_f32_32x32x16_bf16 v[4:19], v[182:185], v[136:139], v[4:19]
	v_mfma_f32_32x32x16_bf16 v[20:35], v[198:201], v[136:139], v[20:35]
	v_mfma_f32_32x32x16_bf16 v[4:19], v[186:189], v[140:143], v[4:19]
	v_mfma_f32_32x32x16_bf16 v[20:35], v[202:205], v[140:143], v[20:35]
	v_mfma_f32_32x32x16_bf16 v[4:19], v[190:193], v[144:147], v[4:19]
	v_mfma_f32_32x32x16_bf16 v[20:35], v[226:229], v[144:147], v[20:35]
	v_lshl_add_u64 v[166:167], v[166:167], 0, s[0:1]
	s_add_u32 s14, s12, 0x1000
	s_addc_u32 s15, s13, 0
	s_add_u32 s16, s12, 0x2000
	s_addc_u32 s17, s13, 0
	global_load_dwordx4 v[178:181], v2, s[12:13]
	global_load_dwordx4 v[182:185], v2, s[12:13] offset:1024
	global_load_dwordx4 v[186:189], v2, s[12:13] offset:2048
	global_load_dwordx4 v[190:193], v2, s[12:13] offset:3072
	global_load_dwordx4 v[194:197], v2, s[14:15]
	global_load_dwordx4 v[198:201], v2, s[14:15] offset:1024
	global_load_dwordx4 v[202:205], v2, s[14:15] offset:2048
	global_load_dwordx4 v[226:229], v2, s[14:15] offset:3072
	global_load_dwordx4 v[230:233], v162, s[16:17]
	global_load_dwordx4 v[234:237], v162, s[16:17] offset:16
	global_load_dwordx4 v[238:241], v164, s[16:17]
	global_load_dwordx4 v[242:245], v164, s[16:17] offset:16
	s_add_i32 s11, s11, 1
	s_cmp_le_u32 s11, s31
	s_cselect_b32 s6, s0, 0
	s_cselect_b32 s7, s1, 0
	s_add_u32 s12, s12, s6
	s_addc_u32 s13, s13, s7
	s_add_i32 s10, s10, 1
	s_cmp_ge_u32 s10, s30
	s_cbranch_scc1 .Lscan_exit
	s_branch .Lscan_loop
